# E46b: both attention tile-halves prefetch QK^T LDS fragments one step ahead (first half steps 5-11 double-buffered; loop-exit address registers recomputed)
# speedup vs baseline: 1.0031x; 1.0031x over previous
.LBB0_2191:
	ds_read_b128 v[64:67], v156 offset:57344
	ds_read_b128 v[200:203], v169 offset:57344
	v_add_u32_e32 v191, v190, v155
	ds_read_b128 v[68:71], v191 offset:12288
	v_add_u32_e32 v193, v190, v175
	ds_read_b128 v[204:207], v193 offset:12288
	v_add_u32_e32 v192, v190, v176
	v_add_f32_e32 v132, 0, v133
	v_add_f32_e32 v132, v214, v132
	s_waitcnt lgkmcnt(3)
	v_mfma_f32_32x32x16_bf16 v[80:95], v[64:67], v[108:111], 0
	v_add_f32_e32 v132, v134, v132
	v_add_f32_e32 v132, v215, v132
	v_add_f32_e32 v132, v213, v132
	v_add_f32_e32 v132, v216, v132
	v_add_f32_e32 v132, v135, v132
	v_add_f32_e32 v132, v212, v132
	v_add_f32_e32 v132, v146, v132
	s_waitcnt lgkmcnt(2)
	v_mfma_f32_32x32x16_bf16 v[80:95], v[200:203], v[104:107], v[80:95]
	ds_read_b128 v[200:203], v168 offset:57344
	v_add_f32_e32 v132, v148, v132
	v_add_f32_e32 v132, v147, v132
	v_add_f32_e32 v132, v149, v132
	v_exp_f32_e32 v126, v126
	v_add_f32_e32 v132, v128, v132
	v_exp_f32_e32 v127, v127
	s_waitcnt lgkmcnt(2)
	v_mfma_f32_32x32x16_bf16 v[64:79], v[68:71], v[108:111], 0
	v_add_f32_e32 v132, v130, v132
	v_exp_f32_e32 v124, v124
	v_add_f32_e32 v132, v129, v132
	v_exp_f32_e32 v125, v125
	v_add_f32_e32 v132, v131, v132
	v_exp_f32_e32 v120, v120
	v_add_f32_e32 v132, v126, v132
	s_waitcnt lgkmcnt(1)
	v_mfma_f32_32x32x16_bf16 v[64:79], v[204:207], v[104:107], v[64:79]
	ds_read_b128 v[204:207], v192 offset:12288
	v_exp_f32_e32 v121, v121
	v_add_f32_e32 v132, v127, v132
	v_exp_f32_e32 v116, v116
	v_add_f32_e32 v132, v124, v132
	v_exp_f32_e32 v117, v117
	v_add_f32_e32 v132, v125, v132
	s_waitcnt lgkmcnt(1)
	v_mfma_f32_32x32x16_bf16 v[80:95], v[200:203], v[100:103], v[80:95]
	v_add_u32_e32 v200, v190, v177
	v_add_u32_e32 v201, v190, v178
	v_exp_f32_e32 v114, v114
	v_add_f32_e32 v132, v120, v132
	v_exp_f32_e32 v115, v115
	v_add_f32_e32 v132, v121, v132
	v_exp_f32_e32 v122, v122
	s_waitcnt lgkmcnt(0)
	v_mfma_f32_32x32x16_bf16 v[64:79], v[204:207], v[100:103], v[64:79]
	ds_read_b128 v[202:205], v167 offset:57344
	ds_read_b128 v[206:209], v200 offset:12288
	v_add_f32_e32 v132, v116, v132
	v_exp_f32_e32 v123, v123
	v_add_f32_e32 v132, v117, v132
	v_exp_f32_e32 v118, v118
	v_add_f32_e32 v132, v114, v132
	s_waitcnt lgkmcnt(1)
	v_mfma_f32_32x32x16_bf16 v[80:95], v[202:205], v[96:99], v[80:95]
	ds_read_b128 v[202:205], v165 offset:57344
	v_exp_f32_e32 v119, v119
	v_add_f32_e32 v132, v115, v132
	v_exp_f32_e32 v112, v112
	v_add_f32_e32 v132, v122, v132
	v_exp_f32_e32 v113, v113
	v_add_f32_e32 v132, v123, v132
	s_waitcnt lgkmcnt(1)
	v_mfma_f32_32x32x16_bf16 v[64:79], v[206:209], v[96:99], v[64:79]
	ds_read_b128 v[206:209], v201 offset:12288
	ds_read_b128 v[224:227], v139
	v_add_f32_e32 v132, v118, v132
	v_add_f32_e32 v132, v119, v132
	v_add_f32_e32 v132, v112, v132
	v_add_u32_e32 v194, v190, v181
	v_add_u32_e32 v195, v190, v182
	v_add_u32_e32 v196, v190, v183
	v_add_u32_e32 v197, v190, v184
	v_add_u32_e32 v198, v190, v185
	v_add_u32_e32 v199, v190, v186
	ds_read_b128 v[244:247], v166 offset:57344
	ds_read_b128 v[248:251], v194 offset:12288
	ds_read_b128 v[220:223], v139 offset:1024
	s_waitcnt lgkmcnt(3)
	v_mfma_f32_32x32x16_bf16 v[64:79], v[206:209], v[224:227], v[64:79]
	v_mfma_f32_32x32x16_bf16 v[80:95], v[202:205], v[224:227], v[80:95]
	ds_read_b128 v[200:203], v158 offset:57344
	ds_read_b128 v[204:207], v195 offset:12288
	ds_read_b128 v[208:211], v139 offset:2048
	s_waitcnt lgkmcnt(3)
	v_mfma_f32_32x32x16_bf16 v[80:95], v[244:247], v[220:223], v[80:95]
	v_mfma_f32_32x32x16_bf16 v[64:79], v[248:251], v[220:223], v[64:79]
	ds_read_b128 v[244:247], v157 offset:57344
	ds_read_b128 v[248:251], v196 offset:12288
	ds_read_b128 v[220:223], v139 offset:3072
	s_waitcnt lgkmcnt(3)
	v_mfma_f32_32x32x16_bf16 v[80:95], v[200:203], v[208:211], v[80:95]
	v_mfma_f32_32x32x16_bf16 v[64:79], v[204:207], v[208:211], v[64:79]
	ds_read_b128 v[200:203], v154 offset:57344
	ds_read_b128 v[204:207], v197 offset:12288
	ds_read_b128 v[208:211], v139 offset:4096
	s_waitcnt lgkmcnt(3)
	v_mfma_f32_32x32x16_bf16 v[80:95], v[244:247], v[220:223], v[80:95]
	v_mfma_f32_32x32x16_bf16 v[64:79], v[248:251], v[220:223], v[64:79]
	ds_read_b128 v[244:247], v153 offset:57344
	ds_read_b128 v[248:251], v198 offset:12288
	ds_read_b128 v[220:223], v139 offset:5120
	s_waitcnt lgkmcnt(3)
	v_mfma_f32_32x32x16_bf16 v[80:95], v[200:203], v[208:211], v[80:95]
	v_mfma_f32_32x32x16_bf16 v[64:79], v[204:207], v[208:211], v[64:79]
	ds_read_b128 v[200:203], v180 offset:57344
	ds_read_b128 v[204:207], v199 offset:12288
	ds_read_b128 v[208:211], v139 offset:6144
	s_waitcnt lgkmcnt(3)
	v_mfma_f32_32x32x16_bf16 v[80:95], v[244:247], v[220:223], v[80:95]
	v_mfma_f32_32x32x16_bf16 v[64:79], v[248:251], v[220:223], v[64:79]
	v_add_u32_e32 v194, v190, v187
	ds_read_b128 v[224:227], v179 offset:57344
	ds_read_b128 v[228:231], v194 offset:12288
	ds_read_b128 v[232:235], v139 offset:7168
	s_waitcnt lgkmcnt(3)
	v_mfma_f32_32x32x16_bf16 v[80:95], v[200:203], v[208:211], v[80:95]
	v_mfma_f32_32x32x16_bf16 v[64:79], v[204:207], v[208:211], v[64:79]
	v_add_f32_e32 v209, v113, v132
	v_mov_b32_e32 v210, v209
	v_cvt_pk_bf16_f32 v132, v133, v214
	v_cvt_pk_bf16_f32 v133, v134, v215
	v_cvt_pk_bf16_f32 v134, v213, v216
	s_waitcnt lgkmcnt(0)
	v_mfma_f32_32x32x16_bf16 v[80:95], v[224:227], v[232:235], v[80:95]
	v_permlane32_swap_b32_e32 v209, v210
	v_cvt_pk_bf16_f32 v135, v135, v212
	v_permlane32_swap_b32_e32 v132, v134
	v_cvt_pk_bf16_f32 v212, v146, v148
	v_cvt_pk_bf16_f32 v213, v147, v149
	v_mfma_f32_32x32x16_bf16 v[64:79], v[228:231], v[232:235], v[64:79]
	v_cvt_pk_bf16_f32 v214, v128, v130
	v_cvt_pk_bf16_f32 v215, v129, v131
	v_cvt_pk_bf16_f32 v216, v126, v127
	v_cvt_pk_bf16_f32 v217, v124, v125
	v_cvt_pk_bf16_f32 v218, v120, v121
	v_cvt_pk_bf16_f32 v219, v116, v117
	v_cvt_pk_bf16_f32 v224, v114, v115
	v_cvt_pk_bf16_f32 v225, v122, v123
	v_cvt_pk_bf16_f32 v226, v118, v119
	v_cvt_pk_bf16_f32 v227, v112, v113
	v_permlane32_swap_b32_e32 v133, v135
	v_permlane32_swap_b32_e32 v212, v214
	v_permlane32_swap_b32_e32 v213, v215
	v_permlane32_swap_b32_e32 v216, v218
	v_permlane32_swap_b32_e32 v217, v219
	v_permlane32_swap_b32_e32 v224, v226
	v_permlane32_swap_b32_e32 v225, v227
	v_lshl_add_u64 v[146:147], s[50:51], 0, v[144:145]
	s_mov_b32 s6, 0x8000
	v_add_co_u32_e32 v112, vcc, s6, v146
	s_mov_b32 s6, 0xa000
	s_nop 0
	v_addc_co_u32_e32 v113, vcc, 0, v147, vcc
	v_add_co_u32_e32 v116, vcc, s6, v146
	v_lshl_add_u64 v[148:149], s[50:51], 0, v[142:143]
	s_nop 0
	v_addc_co_u32_e32 v117, vcc, 0, v147, vcc
	v_add_co_u32_e32 v128, vcc, s64, v148
	global_load_dwordx4 v[112:115], v[112:113], off
	s_nop 0
	global_load_dwordx4 v[116:119], v[116:117], off
	v_addc_co_u32_e32 v129, vcc, 0, v149, vcc
	global_load_dwordx4 v[120:123], v[128:129], off
	global_load_dwordx4 v[124:127], v[128:129], off offset:128
	s_nop 0
	global_load_dwordx4 v[128:131], v[128:129], off offset:256
	ds_read_b64_tr_b16 v[228:229], v152 offset:0
	ds_read_b64_tr_b16 v[230:231], v152 offset:0x800
	ds_read_b64_tr_b16 v[232:233], v152 offset:0x1000
	ds_read_b64_tr_b16 v[234:235], v152 offset:0x1800
	ds_read_b64_tr_b16 v[236:237], v152 offset:0x2000
	ds_read_b64_tr_b16 v[238:239], v152 offset:0x2800
	ds_read_b64_tr_b16 v[240:241], v152 offset:0x3000
	ds_read_b64_tr_b16 v[242:243], v152 offset:0x3800
	s_waitcnt lgkmcnt(0)
	s_nop 0
	v_mfma_f32_32x32x16_bf16 v[0:15], v[132:135], v[228:231], v[0:15]
	ds_read_b64_tr_b16 v[228:229], v152 offset:0x200
	ds_read_b64_tr_b16 v[230:231], v152 offset:0xa00
	v_mfma_f32_32x32x16_bf16 v[0:15], v[212:215], v[232:235], v[0:15]
	ds_read_b64_tr_b16 v[232:233], v152 offset:0x1200
	ds_read_b64_tr_b16 v[234:235], v152 offset:0x1a00
	v_mfma_f32_32x32x16_bf16 v[0:15], v[216:219], v[236:239], v[0:15]
	ds_read_b64_tr_b16 v[236:237], v152 offset:0x2200
	ds_read_b64_tr_b16 v[238:239], v152 offset:0x2a00
	v_mfma_f32_32x32x16_bf16 v[0:15], v[224:227], v[240:243], v[0:15]
	ds_read_b64_tr_b16 v[240:241], v152 offset:0x3200
	ds_read_b64_tr_b16 v[242:243], v152 offset:0x3a00
	s_waitcnt lgkmcnt(0)
	v_mfma_f32_32x32x16_bf16 v[48:63], v[132:135], v[228:231], v[48:63]
	ds_read_b64_tr_b16 v[228:229], v152 offset:0x400
	ds_read_b64_tr_b16 v[230:231], v152 offset:0xc00
	v_mfma_f32_32x32x16_bf16 v[48:63], v[212:215], v[232:235], v[48:63]
	ds_read_b64_tr_b16 v[232:233], v152 offset:0x1400
	ds_read_b64_tr_b16 v[234:235], v152 offset:0x1c00
	v_mfma_f32_32x32x16_bf16 v[48:63], v[216:219], v[236:239], v[48:63]
	ds_read_b64_tr_b16 v[236:237], v152 offset:0x2400
	ds_read_b64_tr_b16 v[238:239], v152 offset:0x2c00
	v_mfma_f32_32x32x16_bf16 v[48:63], v[224:227], v[240:243], v[48:63]
	ds_read_b64_tr_b16 v[240:241], v152 offset:0x3400
	ds_read_b64_tr_b16 v[242:243], v152 offset:0x3c00
	s_waitcnt lgkmcnt(0)
	v_mfma_f32_32x32x16_bf16 v[32:47], v[132:135], v[228:231], v[32:47]
	ds_read_b64_tr_b16 v[228:229], v152 offset:0x600
	ds_read_b64_tr_b16 v[230:231], v152 offset:0xe00
	v_mfma_f32_32x32x16_bf16 v[32:47], v[212:215], v[232:235], v[32:47]
	ds_read_b64_tr_b16 v[232:233], v152 offset:0x1600
	ds_read_b64_tr_b16 v[234:235], v152 offset:0x1e00
	v_mfma_f32_32x32x16_bf16 v[32:47], v[216:219], v[236:239], v[32:47]
	ds_read_b64_tr_b16 v[236:237], v152 offset:0x2600
	ds_read_b64_tr_b16 v[238:239], v152 offset:0x2e00
	v_mfma_f32_32x32x16_bf16 v[32:47], v[224:227], v[240:243], v[32:47]
	ds_read_b64_tr_b16 v[240:241], v152 offset:0x3600
	ds_read_b64_tr_b16 v[242:243], v152 offset:0x3e00
	s_waitcnt lgkmcnt(0)
	v_mfma_f32_32x32x16_bf16 v[16:31], v[132:135], v[228:231], v[16:31]
	v_max_f32_e32 v132, v81, v81
	v_max_f32_e32 v133, v80, v80
	v_max_f32_e32 v132, v133, v132
	v_max3_f32 v132, v132, v82, v83
	v_max3_f32 v132, v132, v84, v85
	v_max3_f32 v132, v132, v86, v87
	v_max3_f32 v132, v132, v88, v89
	v_max3_f32 v132, v132, v90, v91
	v_max3_f32 v132, v132, v92, v93
	v_mfma_f32_32x32x16_bf16 v[16:31], v[212:215], v[232:235], v[16:31]
	v_max3_f32 v132, v132, v94, v95
	v_max3_f32 v132, v132, v64, v65
	v_max3_f32 v132, v132, v66, v67
	v_max3_f32 v132, v132, v68, v69
	v_max3_f32 v132, v132, v70, v71
	v_max3_f32 v132, v132, v72, v73
	v_max3_f32 v132, v132, v74, v75
	v_max3_f32 v132, v132, v76, v77
	v_mfma_f32_32x32x16_bf16 v[16:31], v[216:219], v[236:239], v[16:31]
	v_max3_f32 v132, v132, v78, v79
	v_mov_b32_e32 v133, v132
	s_nop 1
	v_permlane32_swap_b32_e32 v132, v133
	v_max_f32_e32 v133, v133, v133
	v_max_f32_e32 v132, v132, v132
	v_max_f32_e32 v132, v132, v133
	v_sub_f32_e32 v133, v132, v188
	v_cmp_ge_f32_e32 vcc, s1, v133
	v_max_f32_e32 v133, v188, v188
	v_max_f32_e32 v132, v133, v132
	v_mfma_f32_32x32x16_bf16 v[16:31], v[224:227], v[240:243], v[16:31]
	v_sub_f32_e32 v133, v188, v132
	v_mul_f32_e32 v133, 0x3dd53b94, v133
	v_exp_f32_e32 v133, v133
	s_cmp_eq_u64 vcc, exec
	s_cselect_b64 s[6:7], -1, 0
	s_barrier
	s_waitcnt vmcnt(0)
	v_cndmask_b32_e64 v211, v133, 1.0, s[6:7]
	v_cmp_gt_f32_e32 vcc, 1.0, v211
	s_waitcnt vmcnt(4)
	ds_write_b128 v163, v[112:115]
	s_waitcnt vmcnt(3)
	ds_write_b128 v164, v[116:119]
	s_waitcnt vmcnt(2)
	ds_write_b128 v159, v[120:123] offset:32768
	s_waitcnt vmcnt(1)
	ds_write_b128 v159, v[124:127] offset:32896
	s_waitcnt vmcnt(0)
	ds_write_b128 v159, v[128:131] offset:33024
	s_cbranch_vccz .LBB0_2195
	s_and_saveexec_b64 s[10:11], s[4:5]
	ds_write_b32 v174, v211 offset:128
	s_or_b64 exec, exec, s[10:11]
	s_waitcnt lgkmcnt(0)
	v_add_u32_e32 v124, v137, v160
	ds_read_b128 v[112:115], v124 offset:224
	ds_read_b128 v[116:119], v124 offset:192
	ds_read_b128 v[120:123], v124 offset:160
	ds_read_b128 v[124:127], v124 offset:128
	s_waitcnt lgkmcnt(3)
	v_pk_mul_f32 v[12:13], v[12:13], v[112:113]
	s_waitcnt lgkmcnt(2)
	v_pk_mul_f32 v[8:9], v[8:9], v[116:117]
	s_waitcnt lgkmcnt(1)
	v_pk_mul_f32 v[4:5], v[4:5], v[120:121]
	v_pk_mul_f32 v[14:15], v[14:15], v[114:115]
	v_pk_mul_f32 v[10:11], v[10:11], v[118:119]
	v_pk_mul_f32 v[6:7], v[6:7], v[122:123]
	s_waitcnt lgkmcnt(0)
	v_pk_mul_f32 v[2:3], v[2:3], v[126:127]
	v_pk_mul_f32 v[0:1], v[0:1], v[124:125]
	v_pk_mul_f32 v[60:61], v[60:61], v[112:113]
	v_pk_mul_f32 v[56:57], v[56:57], v[116:117]
	v_pk_mul_f32 v[52:53], v[52:53], v[120:121]
	v_pk_mul_f32 v[62:63], v[62:63], v[114:115]
	v_pk_mul_f32 v[58:59], v[58:59], v[118:119]
	v_pk_mul_f32 v[54:55], v[54:55], v[122:123]
	v_pk_mul_f32 v[50:51], v[50:51], v[126:127]
	v_pk_mul_f32 v[48:49], v[48:49], v[124:125]
	v_pk_mul_f32 v[44:45], v[44:45], v[112:113]
	v_pk_mul_f32 v[40:41], v[40:41], v[116:117]
	v_pk_mul_f32 v[36:37], v[36:37], v[120:121]
	v_pk_mul_f32 v[46:47], v[46:47], v[114:115]
	v_pk_mul_f32 v[42:43], v[42:43], v[118:119]
	v_pk_mul_f32 v[38:39], v[38:39], v[122:123]
	v_pk_mul_f32 v[34:35], v[34:35], v[126:127]
	v_pk_mul_f32 v[32:33], v[32:33], v[124:125]
	v_pk_mul_f32 v[28:29], v[28:29], v[112:113]
	v_pk_mul_f32 v[24:25], v[24:25], v[116:117]
	v_pk_mul_f32 v[20:21], v[20:21], v[120:121]
	v_pk_mul_f32 v[30:31], v[30:31], v[114:115]
	v_pk_mul_f32 v[26:27], v[26:27], v[118:119]
	v_pk_mul_f32 v[22:23], v[22:23], v[122:123]
	v_pk_mul_f32 v[18:19], v[18:19], v[126:127]
	v_pk_mul_f32 v[16:17], v[16:17], v[124:125]

.LBB0_2201:
	v_add_u32_e32 v200, v190, v177
	v_add_u32_e32 v201, v190, v178
	v_add_u32_e32 v202, v190, v182
	v_add_u32_e32 v203, v190, v183
	v_add_u32_e32 v204, v190, v181
	v_add_u32_e32 v205, v190, v185
	v_add_u32_e32 v206, v190, v184
	v_add_u32_e32 v207, v190, v186
	v_add_u32_e32 v208, v190, v187
	v_mov_b32_e32 v194, 0x1000
	v_mov_b32_e32 v195, 1
	v_mov_b32_e32 v196, s94
	v_mbcnt_lo_u32_b32 v197, -1, 0
	v_mbcnt_hi_u32_b32 v197, -1, v197
	v_mov_b32_e32 v198, 0xf149f2ca
	v_mov_b32_e32 v199, v197
	v_mov_b32_e32 v220, 0
	v_mov_b32_e32 v221, 0
	v_mov_b32_e32 v222, 0
	v_mov_b32_e32 v223, 0
	ds_read_b128 v[64:67], v156 offset:57344
	ds_read_b128 v[68:71], v191 offset:12288
	v_exp_f32_e32 v116, v116
	v_exp_f32_e32 v117, v117
	v_exp_f32_e32 v114, v114
	s_waitcnt lgkmcnt(1)
	v_mfma_f32_32x32x16_bf16 v[80:95], v[64:67], v[108:111], 0
	v_exp_f32_e32 v115, v115
	v_exp_f32_e32 v118, v118
	v_exp_f32_e32 v119, v119
	v_exp_f32_e32 v113, v113
	s_waitcnt lgkmcnt(0)
	v_mfma_f32_32x32x16_bf16 v[64:79], v[68:71], v[108:111], 0
	ds_read_b128 v[108:111], v169 offset:57344
	ds_read_b128 v[142:145], v193 offset:12288
	s_waitcnt lgkmcnt(1)
	v_mfma_f32_32x32x16_bf16 v[80:95], v[108:111], v[104:107], v[80:95]
	s_waitcnt lgkmcnt(0)
	v_mfma_f32_32x32x16_bf16 v[64:79], v[142:145], v[104:107], v[64:79]
	ds_read_b128 v[104:107], v168 offset:57344
	ds_read_b128 v[108:111], v192 offset:12288
	s_waitcnt lgkmcnt(1)
	v_mfma_f32_32x32x16_bf16 v[80:95], v[104:107], v[100:103], v[80:95]
	s_waitcnt lgkmcnt(0)
	v_mfma_f32_32x32x16_bf16 v[64:79], v[108:111], v[100:103], v[64:79]
	ds_read_b128 v[100:103], v167 offset:57344
	ds_read_b128 v[104:107], v200 offset:12288
	v_exp_f32_e32 v108, v124
	v_exp_f32_e32 v109, v125
	v_exp_f32_e32 v110, v120
	v_exp_f32_e32 v111, v121
	v_exp_f32_e32 v120, v122
	v_exp_f32_e32 v121, v123
	s_waitcnt lgkmcnt(1)
	v_mfma_f32_32x32x16_bf16 v[80:95], v[100:103], v[96:99], v[80:95]
	v_exp_f32_e32 v122, v112
	s_waitcnt lgkmcnt(0)
	v_mfma_f32_32x32x16_bf16 v[64:79], v[104:107], v[96:99], v[64:79]
	ds_read_b128 v[96:99], v165 offset:57344
	ds_read_b128 v[100:103], v201 offset:12288
	ds_read_b128 v[104:107], v139
	s_waitcnt lgkmcnt(0)
	v_mfma_f32_32x32x16_bf16 v[80:95], v[96:99], v[104:107], v[80:95]
	v_mfma_f32_32x32x16_bf16 v[64:79], v[100:103], v[104:107], v[64:79]
	ds_read_b128 v[96:99], v166 offset:57344
	ds_read_b128 v[100:103], v204 offset:12288
	ds_read_b128 v[104:107], v139 offset:1024
	s_waitcnt lgkmcnt(0)
	v_mfma_f32_32x32x16_bf16 v[80:95], v[96:99], v[104:107], v[80:95]
	v_mfma_f32_32x32x16_bf16 v[64:79], v[100:103], v[104:107], v[64:79]
	ds_read_b128 v[96:99], v158 offset:57344
	ds_read_b128 v[100:103], v202 offset:12288
	ds_read_b128 v[104:107], v139 offset:2048
	s_waitcnt lgkmcnt(0)
	v_mfma_f32_32x32x16_bf16 v[80:95], v[96:99], v[104:107], v[80:95]
	v_mfma_f32_32x32x16_bf16 v[64:79], v[100:103], v[104:107], v[64:79]
	ds_read_b128 v[96:99], v157 offset:57344
	ds_read_b128 v[100:103], v203 offset:12288
	ds_read_b128 v[104:107], v139 offset:3072
	s_waitcnt lgkmcnt(0)
	v_mfma_f32_32x32x16_bf16 v[80:95], v[96:99], v[104:107], v[80:95]
	v_mfma_f32_32x32x16_bf16 v[64:79], v[100:103], v[104:107], v[64:79]
	ds_read_b128 v[96:99], v154 offset:57344
	ds_read_b128 v[100:103], v206 offset:12288
	ds_read_b128 v[104:107], v139 offset:4096
	s_waitcnt lgkmcnt(0)
	v_mfma_f32_32x32x16_bf16 v[80:95], v[96:99], v[104:107], v[80:95]
	v_mfma_f32_32x32x16_bf16 v[64:79], v[100:103], v[104:107], v[64:79]
	ds_read_b128 v[96:99], v153 offset:57344
	ds_read_b128 v[100:103], v205 offset:12288
	ds_read_b128 v[104:107], v139 offset:5120
	s_waitcnt lgkmcnt(0)
	v_mfma_f32_32x32x16_bf16 v[80:95], v[96:99], v[104:107], v[80:95]
	v_mfma_f32_32x32x16_bf16 v[64:79], v[100:103], v[104:107], v[64:79]
	ds_read_b128 v[96:99], v180 offset:57344
	ds_read_b128 v[100:103], v207 offset:12288
	ds_read_b128 v[104:107], v139 offset:6144
	s_waitcnt lgkmcnt(0)
	v_mfma_f32_32x32x16_bf16 v[80:95], v[96:99], v[104:107], v[80:95]
	v_mfma_f32_32x32x16_bf16 v[64:79], v[100:103], v[104:107], v[64:79]
	ds_read_b128 v[96:99], v179 offset:57344
	ds_read_b128 v[100:103], v208 offset:12288
	ds_read_b128 v[104:107], v139 offset:7168
	s_waitcnt lgkmcnt(0)
	v_mfma_f32_32x32x16_bf16 v[80:95], v[96:99], v[104:107], v[80:95]
	v_add_f32_e32 v96, 0, v133
	v_add_f32_e32 v96, v214, v96
	v_add_f32_e32 v96, v134, v96
	v_add_f32_e32 v96, v215, v96
	v_add_f32_e32 v96, v213, v96
	v_add_f32_e32 v96, v216, v96
	v_add_f32_e32 v96, v135, v96
	v_add_f32_e32 v96, v212, v96
	v_add_f32_e32 v96, v146, v96
	v_add_f32_e32 v96, v148, v96
	v_add_f32_e32 v96, v147, v96
	v_add_f32_e32 v96, v149, v96
	v_mfma_f32_32x32x16_bf16 v[64:79], v[100:103], v[104:107], v[64:79]
	v_exp_f32_e32 v106, v126
	v_add_f32_e32 v96, v128, v96
	v_exp_f32_e32 v107, v127
	v_add_f32_e32 v96, v130, v96
	v_add_f32_e32 v96, v129, v96
	v_add_f32_e32 v96, v131, v96
	v_add_f32_e32 v96, v106, v96
	v_add_f32_e32 v96, v107, v96
	v_add_f32_e32 v96, v108, v96
	v_add_f32_e32 v96, v109, v96
	v_add_f32_e32 v96, v110, v96
	v_add_f32_e32 v96, v111, v96
	v_add_f32_e32 v96, v116, v96
	v_add_f32_e32 v96, v117, v96
	v_add_f32_e32 v96, v114, v96
	v_add_f32_e32 v96, v115, v96
	v_add_f32_e32 v96, v120, v96
	v_add_f32_e32 v96, v121, v96
	v_add_f32_e32 v96, v118, v96
	v_add_f32_e32 v96, v119, v96
	v_add_f32_e32 v96, v122, v96
	v_add_f32_e32 v96, v113, v96
	v_mov_b32_e32 v97, v96
	v_cvt_pk_bf16_f32 v98, v133, v214
	v_cvt_pk_bf16_f32 v99, v134, v215
	v_cvt_pk_bf16_f32 v100, v213, v216
	v_cvt_pk_bf16_f32 v101, v135, v212
	s_nop 1
	v_permlane32_swap_b32_e32 v96, v97
	v_permlane32_swap_b32_e32 v98, v100
	v_permlane32_swap_b32_e32 v99, v101
	v_cvt_pk_bf16_f32 v102, v146, v148
	v_cvt_pk_bf16_f32 v103, v147, v149
	v_cvt_pk_bf16_f32 v104, v128, v130
	v_cvt_pk_bf16_f32 v105, v129, v131
	v_cvt_pk_bf16_f32 v106, v106, v107
	v_cvt_pk_bf16_f32 v107, v108, v109
	v_cvt_pk_bf16_f32 v108, v110, v111
	v_cvt_pk_bf16_f32 v109, v116, v117
	v_cvt_pk_bf16_f32 v110, v114, v115
	v_cvt_pk_bf16_f32 v111, v120, v121
	v_cvt_pk_bf16_f32 v112, v118, v119
	v_cvt_pk_bf16_f32 v113, v122, v113
	s_nop 0
	v_permlane32_swap_b32_e32 v102, v104
	v_permlane32_swap_b32_e32 v103, v105
	v_permlane32_swap_b32_e32 v106, v108
	v_permlane32_swap_b32_e32 v107, v109
	v_permlane32_swap_b32_e32 v110, v112
	v_permlane32_swap_b32_e32 v111, v113
	ds_read_b64_tr_b16 v[114:115], v152 offset:0
	ds_read_b64_tr_b16 v[116:117], v152 offset:0x800
	ds_read_b64_tr_b16 v[118:119], v152 offset:0x1000
	ds_read_b64_tr_b16 v[120:121], v152 offset:0x1800
	ds_read_b64_tr_b16 v[122:123], v152 offset:0x2000
	ds_read_b64_tr_b16 v[124:125], v152 offset:0x2800
	ds_read_b64_tr_b16 v[126:127], v152 offset:0x3000
	ds_read_b64_tr_b16 v[128:129], v152 offset:0x3800
	s_waitcnt lgkmcnt(0)
	s_nop 0
	v_mfma_f32_32x32x16_bf16 v[0:15], v[98:101], v[114:117], v[0:15]
	ds_read_b64_tr_b16 v[114:115], v152 offset:0x200
	ds_read_b64_tr_b16 v[116:117], v152 offset:0xa00
	v_mfma_f32_32x32x16_bf16 v[0:15], v[102:105], v[118:121], v[0:15]
	ds_read_b64_tr_b16 v[118:119], v152 offset:0x1200
	ds_read_b64_tr_b16 v[120:121], v152 offset:0x1a00
	v_mfma_f32_32x32x16_bf16 v[0:15], v[106:109], v[122:125], v[0:15]
	ds_read_b64_tr_b16 v[122:123], v152 offset:0x2200
	ds_read_b64_tr_b16 v[124:125], v152 offset:0x2a00
	v_mfma_f32_32x32x16_bf16 v[0:15], v[110:113], v[126:129], v[0:15]
	ds_read_b64_tr_b16 v[126:127], v152 offset:0x3200
	ds_read_b64_tr_b16 v[128:129], v152 offset:0x3a00
	s_waitcnt lgkmcnt(0)
	v_mfma_f32_32x32x16_bf16 v[48:63], v[98:101], v[114:117], v[48:63]
	ds_read_b64_tr_b16 v[114:115], v152 offset:0x400
	ds_read_b64_tr_b16 v[116:117], v152 offset:0xc00
	v_mfma_f32_32x32x16_bf16 v[48:63], v[102:105], v[118:121], v[48:63]
	ds_read_b64_tr_b16 v[118:119], v152 offset:0x1400
	ds_read_b64_tr_b16 v[120:121], v152 offset:0x1c00
	v_mfma_f32_32x32x16_bf16 v[48:63], v[106:109], v[122:125], v[48:63]
	ds_read_b64_tr_b16 v[122:123], v152 offset:0x2400
	ds_read_b64_tr_b16 v[124:125], v152 offset:0x2c00
	v_mfma_f32_32x32x16_bf16 v[48:63], v[110:113], v[126:129], v[48:63]
	ds_read_b64_tr_b16 v[126:127], v152 offset:0x3400
	ds_read_b64_tr_b16 v[128:129], v152 offset:0x3c00
	s_waitcnt lgkmcnt(0)
	v_mfma_f32_32x32x16_bf16 v[32:47], v[98:101], v[114:117], v[32:47]
	ds_read_b64_tr_b16 v[114:115], v152 offset:0x600
	ds_read_b64_tr_b16 v[116:117], v152 offset:0xe00
	v_mfma_f32_32x32x16_bf16 v[32:47], v[102:105], v[118:121], v[32:47]
	ds_read_b64_tr_b16 v[118:119], v152 offset:0x1600
	ds_read_b64_tr_b16 v[120:121], v152 offset:0x1e00
	v_mfma_f32_32x32x16_bf16 v[32:47], v[106:109], v[122:125], v[32:47]
	ds_read_b64_tr_b16 v[122:123], v152 offset:0x2600
	ds_read_b64_tr_b16 v[124:125], v152 offset:0x2e00
	v_mfma_f32_32x32x16_bf16 v[32:47], v[110:113], v[126:129], v[32:47]
	ds_read_b64_tr_b16 v[126:127], v152 offset:0x3600
	ds_read_b64_tr_b16 v[128:129], v152 offset:0x3e00
	s_waitcnt lgkmcnt(0)
	v_mfma_f32_32x32x16_bf16 v[16:31], v[98:101], v[114:117], v[16:31]
	v_max_f32_e32 v98, v81, v81
	v_max_f32_e32 v99, v80, v80
	v_max_f32_e32 v98, v99, v98
	v_max3_f32 v98, v98, v82, v83
	v_max3_f32 v98, v98, v84, v85
	v_max3_f32 v98, v98, v86, v87
	v_max3_f32 v98, v98, v88, v89
	v_max3_f32 v98, v98, v90, v91
	v_max3_f32 v98, v98, v92, v93
	v_mfma_f32_32x32x16_bf16 v[16:31], v[102:105], v[118:121], v[16:31]
	v_max3_f32 v98, v98, v94, v95
	v_max3_f32 v98, v98, v64, v65
	v_max3_f32 v98, v98, v66, v67
	v_max3_f32 v98, v98, v68, v69
	v_max3_f32 v98, v98, v70, v71
	v_max3_f32 v98, v98, v72, v73
	v_max3_f32 v98, v98, v74, v75
	v_max3_f32 v98, v98, v76, v77
	v_mfma_f32_32x32x16_bf16 v[16:31], v[106:109], v[122:125], v[16:31]
	v_max3_f32 v98, v98, v78, v79
	v_mov_b32_e32 v99, v98
	s_nop 1
	v_permlane32_swap_b32_e32 v98, v99
	v_max_f32_e32 v99, v99, v99
	v_max_f32_e32 v98, v98, v98
	v_max_f32_e32 v98, v98, v99
	v_sub_f32_e32 v99, v98, v188
	v_cmp_ge_f32_e32 vcc, s1, v99
	v_max_f32_e32 v99, v188, v188
	v_max_f32_e32 v99, v99, v98
	v_mfma_f32_32x32x16_bf16 v[16:31], v[110:113], v[126:129], v[16:31]
	v_sub_f32_e32 v98, v188, v99
	v_mul_f32_e32 v98, 0x3dd53b94, v98
	v_exp_f32_e32 v98, v98
	s_cmp_eq_u64 vcc, exec
	s_cselect_b64 s[6:7], -1, 0
	v_cndmask_b32_e64 v98, v98, 1.0, s[6:7]
	v_cmp_gt_f32_e32 vcc, 1.0, v98
	s_barrier
	s_cbranch_vccz .LBB0_2205
	s_and_saveexec_b64 s[10:11], s[4:5]
	ds_write_b32 v174, v98 offset:128
	s_or_b64 exec, exec, s[10:11]
	s_waitcnt lgkmcnt(0)
	v_add_u32_e32 v112, v137, v160
	ds_read_b128 v[100:103], v112 offset:224
	ds_read_b128 v[104:107], v112 offset:192
	ds_read_b128 v[108:111], v112 offset:160
	ds_read_b128 v[112:115], v112 offset:128
	s_waitcnt lgkmcnt(3)
	v_pk_mul_f32 v[12:13], v[12:13], v[100:101]
	s_waitcnt lgkmcnt(2)
	v_pk_mul_f32 v[8:9], v[8:9], v[104:105]
	s_waitcnt lgkmcnt(1)
	v_pk_mul_f32 v[4:5], v[4:5], v[108:109]
	v_pk_mul_f32 v[14:15], v[14:15], v[102:103]
	v_pk_mul_f32 v[10:11], v[10:11], v[106:107]
	v_pk_mul_f32 v[6:7], v[6:7], v[110:111]
	s_waitcnt lgkmcnt(0)
	v_pk_mul_f32 v[2:3], v[2:3], v[114:115]
	v_pk_mul_f32 v[0:1], v[0:1], v[112:113]
	v_pk_mul_f32 v[60:61], v[60:61], v[100:101]
	v_pk_mul_f32 v[56:57], v[56:57], v[104:105]
	v_pk_mul_f32 v[52:53], v[52:53], v[108:109]
	v_pk_mul_f32 v[62:63], v[62:63], v[102:103]
	v_pk_mul_f32 v[58:59], v[58:59], v[106:107]
	v_pk_mul_f32 v[54:55], v[54:55], v[110:111]
	v_pk_mul_f32 v[50:51], v[50:51], v[114:115]
	v_pk_mul_f32 v[48:49], v[48:49], v[112:113]
	v_pk_mul_f32 v[44:45], v[44:45], v[100:101]
	v_pk_mul_f32 v[40:41], v[40:41], v[104:105]
	v_pk_mul_f32 v[36:37], v[36:37], v[108:109]
	v_pk_mul_f32 v[46:47], v[46:47], v[102:103]
	v_pk_mul_f32 v[42:43], v[42:43], v[106:107]
	v_pk_mul_f32 v[38:39], v[38:39], v[110:111]
	v_pk_mul_f32 v[34:35], v[34:35], v[114:115]
	v_pk_mul_f32 v[32:33], v[32:33], v[112:113]
	v_pk_mul_f32 v[28:29], v[28:29], v[100:101]
	v_pk_mul_f32 v[24:25], v[24:25], v[104:105]
	v_pk_mul_f32 v[20:21], v[20:21], v[108:109]
	v_pk_mul_f32 v[30:31], v[30:31], v[102:103]
	v_pk_mul_f32 v[26:27], v[26:27], v[106:107]
	v_pk_mul_f32 v[22:23], v[22:23], v[110:111]
	v_pk_mul_f32 v[18:19], v[18:19], v[114:115]
	v_pk_mul_f32 v[16:17], v[16:17], v[112:113]
